# v31 + redundant end-of-pass workgroup barrier removed (covered by the last tile's mid-step barrier) in A and B
# speedup vs baseline: 1.0003x; 1.0000x over previous
; #define SBAR() __builtin_amdgcn_sched_barrier(0)
; template <int DK, int LDK, bool BIAS, bool NOMAX> ...
;     ...
;   STEPT(pB0, pB1, pA0, pA1, alA, alB, NT - 1);
;   if constexpr (NOMAX) { PK4R(pB0, 0, pa[0]); PK4R(pB0, 8, pa[1]); PK4R(pB1, 0, pa[2]); PK4R(pB1, 8, pa[3]); }
;   else finishSM<false>(pB0, pB1, alB, l_reg, pa[0], pa[1], pa[2], pa[3]);
;   SBAR();
;   pv_d0(o, vb0 + sp, pa[0], pa[1], pa[2], pa[3]);
;   l_out = l_reg;
; __device__ __forceinline__ void item_a(bf16_t* OUT, const bf16_t* QA, const bf16_t* KA, const bf16_t* VA, const bf16_t* ZA, const float* tabA, const float* subln, const float lam, ...
;     ...
;     flash_pass<64, 1024, true, true>(qr, Kh + mp * 64, Vh, S, lds, o, l, qlo, b_neg, b_pos);
;     if (!(l > 1e-30f && l < 1e30f)) *badf = 1u;
;     __syncthreads(); const unsigned redo = (PROBE == 20) ? 1u : *badf; __syncthreads();
.LBB0_256:
	s_waitcnt vmcnt(0) lgkmcnt(0)
	v_add_f32_e32 v7, v2, v3
	v_fmac_f32_e32 v7, v186, v0
	v_cvt_pk_bf16_f32 v2, v128, v129
	v_cvt_pk_bf16_f32 v3, v130, v131
	v_cvt_pk_bf16_f32 v4, v132, v133
	v_cvt_pk_bf16_f32 v5, v134, v135
	v_cvt_pk_bf16_f32 v8, v136, v137
	v_cvt_pk_bf16_f32 v9, v138, v139
	v_cvt_pk_bf16_f32 v10, v140, v141
	v_cvt_pk_bf16_f32 v11, v142, v143
	v_cvt_pk_bf16_f32 v12, v112, v113
	v_cvt_pk_bf16_f32 v13, v114, v115
	v_cvt_pk_bf16_f32 v14, v116, v117
	v_cvt_pk_bf16_f32 v15, v118, v119
	v_cvt_pk_bf16_f32 v80, v120, v121
	v_cvt_pk_bf16_f32 v81, v122, v123
	v_cvt_pk_bf16_f32 v82, v124, v125
	v_cvt_pk_bf16_f32 v83, v126, v127
	s_nop 0
	v_permlane32_swap_b32_e32 v2, v4
	v_permlane32_swap_b32_e32 v3, v5
	v_permlane32_swap_b32_e32 v8, v10
	v_permlane32_swap_b32_e32 v9, v11
	v_permlane32_swap_b32_e32 v12, v14
	v_permlane32_swap_b32_e32 v13, v15
	v_permlane32_swap_b32_e32 v80, v82
	v_permlane32_swap_b32_e32 v81, v83
	s_cmp_lg_u32 s52, -1
	s_cselect_b32 s0, s52, 0
	s_addk_i32 s0, 0x4000
	v_add_u32_e32 v0, s0, v170
	ds_read_b64_tr_b16 v[84:85], v0 offset:0
	ds_read_b64_tr_b16 v[86:87], v0 offset:0x800
	ds_read_b64_tr_b16 v[88:89], v0 offset:0x1000
	ds_read_b64_tr_b16 v[90:91], v0 offset:0x1800
	ds_read_b64_tr_b16 v[92:93], v0 offset:0x2000
	ds_read_b64_tr_b16 v[94:95], v0 offset:0x2800
	ds_read_b64_tr_b16 v[96:97], v0 offset:0x3000
	ds_read_b64_tr_b16 v[98:99], v0 offset:0x3800
	s_waitcnt lgkmcnt(0)
	s_nop 0
	v_mfma_f32_32x32x16_bf16 v[16:31], v[2:5], v[84:87], v[16:31]
	ds_read_b64_tr_b16 v[84:85], v0 offset:0x200
	ds_read_b64_tr_b16 v[86:87], v0 offset:0xa00
	v_mfma_f32_32x32x16_bf16 v[16:31], v[8:11], v[88:91], v[16:31]
	ds_read_b64_tr_b16 v[88:89], v0 offset:0x1200
	ds_read_b64_tr_b16 v[90:91], v0 offset:0x1a00
	v_mfma_f32_32x32x16_bf16 v[16:31], v[12:15], v[92:95], v[16:31]
	ds_read_b64_tr_b16 v[92:93], v0 offset:0x2200
	ds_read_b64_tr_b16 v[94:95], v0 offset:0x2a00
	v_mfma_f32_32x32x16_bf16 v[16:31], v[80:83], v[96:99], v[16:31]
	ds_read_b64_tr_b16 v[96:97], v0 offset:0x3200
	ds_read_b64_tr_b16 v[98:99], v0 offset:0x3a00
	s_waitcnt lgkmcnt(0)
	v_mfma_f32_32x32x16_bf16 v[32:47], v[2:5], v[84:87], v[32:47]
	ds_read_b64_tr_b16 v[84:85], v0 offset:0x400
	ds_read_b64_tr_b16 v[86:87], v0 offset:0xc00
	v_mfma_f32_32x32x16_bf16 v[32:47], v[8:11], v[88:91], v[32:47]
	ds_read_b64_tr_b16 v[88:89], v0 offset:0x1400
	ds_read_b64_tr_b16 v[90:91], v0 offset:0x1c00
	v_mfma_f32_32x32x16_bf16 v[32:47], v[12:15], v[92:95], v[32:47]
	ds_read_b64_tr_b16 v[92:93], v0 offset:0x2400
	ds_read_b64_tr_b16 v[94:95], v0 offset:0x2c00
	v_mfma_f32_32x32x16_bf16 v[32:47], v[80:83], v[96:99], v[32:47]
	ds_read_b64_tr_b16 v[96:97], v0 offset:0x3400
	ds_read_b64_tr_b16 v[98:99], v0 offset:0x3c00
	s_waitcnt lgkmcnt(0)
	v_mfma_f32_32x32x16_bf16 v[48:63], v[2:5], v[84:87], v[48:63]
	ds_read_b64_tr_b16 v[84:85], v0 offset:0x600
	ds_read_b64_tr_b16 v[86:87], v0 offset:0xe00
	v_mfma_f32_32x32x16_bf16 v[48:63], v[8:11], v[88:91], v[48:63]
	ds_read_b64_tr_b16 v[88:89], v0 offset:0x1600
	ds_read_b64_tr_b16 v[90:91], v0 offset:0x1e00
	v_mfma_f32_32x32x16_bf16 v[48:63], v[12:15], v[92:95], v[48:63]
	ds_read_b64_tr_b16 v[92:93], v0 offset:0x2600
	ds_read_b64_tr_b16 v[94:95], v0 offset:0x2e00
	v_mfma_f32_32x32x16_bf16 v[48:63], v[80:83], v[96:99], v[48:63]
	ds_read_b64_tr_b16 v[96:97], v0 offset:0x3600
	ds_read_b64_tr_b16 v[98:99], v0 offset:0x3e00
	s_waitcnt lgkmcnt(0)
	v_mfma_f32_32x32x16_bf16 v[64:79], v[2:5], v[84:87], v[64:79]
	v_cmp_nlt_f32_e32 vcc, s27, v7
	v_cmp_ngt_f32_e64 s[0:1], s26, v7
	s_or_b64 s[2:3], vcc, s[0:1]
	v_mfma_f32_32x32x16_bf16 v[64:79], v[8:11], v[88:91], v[64:79]
	v_mfma_f32_32x32x16_bf16 v[64:79], v[12:15], v[92:95], v[64:79]
	v_mfma_f32_32x32x16_bf16 v[64:79], v[80:83], v[96:99], v[64:79]
	s_and_saveexec_b64 s[0:1], s[2:3]
	s_cbranch_execz .LBB0_258
	s_mov_b64 s[2:3], src_shared_base
	s_add_i32 s2, 0, 0x1d000
	s_cmp_lg_u32 s2, -1
	s_cselect_b32 s2, s2, 0
	s_cselect_b32 s3, s3, 0
	v_mov_b32_e32 v2, s2
	v_mov_b32_e32 v3, s3
	flat_store_dword v[2:3], v175 sc0 sc1
	s_waitcnt vmcnt(0)

; #define SBAR() __builtin_amdgcn_sched_barrier(0)
; template <int DK, int LDK, bool BIAS, bool NOMAX> ...
;     ...
;   STEPT(pB0, pB1, pA0, pA1, alA, alB, NT - 1);
;   if constexpr (NOMAX) { PK4R(pB0, 0, pa[0]); PK4R(pB0, 8, pa[1]); PK4R(pB1, 0, pa[2]); PK4R(pB1, 8, pa[3]); }
;   else finishSM<false>(pB0, pB1, alB, l_reg, pa[0], pa[1], pa[2], pa[3]);
;   SBAR();
;   pv_d0(o, vb0 + sp, pa[0], pa[1], pa[2], pa[3]);
;   l_out = l_reg;
; __device__ __forceinline__ void item_a(bf16_t* OUT, const bf16_t* QA, const bf16_t* KA, const bf16_t* VA, const bf16_t* ZA, const float* tabA, const float* subln, const float lam, ...
;     ...
;     flash_pass<64, 1024, true, true>(qr, Kh + mp * 64, Vh, S, lds, o, l, qlo, b_neg, b_pos);
;     if (!(l > 1e-30f && l < 1e30f)) *badf = 1u;
;     __syncthreads(); const unsigned redo = (PROBE == 20) ? 1u : *badf; __syncthreads();
.LBB0_349:
	s_waitcnt vmcnt(0) lgkmcnt(0)
	v_add_f32_e32 v7, v2, v3
	s_cmp_lg_u32 s52, -1
	v_fmac_f32_e32 v7, v186, v0
	s_cselect_b32 s0, s52, 0
	v_cvt_pk_bf16_f32 v2, v128, v129
	v_cvt_pk_bf16_f32 v3, v130, v131
	v_cvt_pk_bf16_f32 v4, v132, v133
	v_cvt_pk_bf16_f32 v5, v134, v135
	v_cvt_pk_bf16_f32 v8, v136, v137
	v_cvt_pk_bf16_f32 v9, v138, v139
	v_cvt_pk_bf16_f32 v10, v140, v141
	v_cvt_pk_bf16_f32 v11, v142, v143
	v_cvt_pk_bf16_f32 v12, v112, v113
	v_cvt_pk_bf16_f32 v13, v114, v115
	v_cvt_pk_bf16_f32 v14, v116, v117
	v_cvt_pk_bf16_f32 v15, v118, v119
	v_cvt_pk_bf16_f32 v80, v120, v121
	v_cvt_pk_bf16_f32 v81, v122, v123
	v_cvt_pk_bf16_f32 v82, v124, v125
	v_cvt_pk_bf16_f32 v83, v126, v127
	v_add_u32_e32 v0, s0, v171
	v_permlane32_swap_b32_e32 v2, v4
	v_permlane32_swap_b32_e32 v3, v5
	v_permlane32_swap_b32_e32 v8, v10
	v_permlane32_swap_b32_e32 v9, v11
	v_permlane32_swap_b32_e32 v12, v14
	v_permlane32_swap_b32_e32 v13, v15
	v_permlane32_swap_b32_e32 v80, v82
	v_permlane32_swap_b32_e32 v81, v83
	ds_read_b64_tr_b16 v[84:85], v0 offset:0
	ds_read_b64_tr_b16 v[86:87], v0 offset:0x800
	ds_read_b64_tr_b16 v[88:89], v0 offset:0x1000
	ds_read_b64_tr_b16 v[90:91], v0 offset:0x1800
	ds_read_b64_tr_b16 v[92:93], v0 offset:0x2000
	ds_read_b64_tr_b16 v[94:95], v0 offset:0x2800
	ds_read_b64_tr_b16 v[96:97], v0 offset:0x3000
	ds_read_b64_tr_b16 v[98:99], v0 offset:0x3800
	s_waitcnt lgkmcnt(0)
	s_nop 0
	v_mfma_f32_32x32x16_bf16 v[16:31], v[2:5], v[84:87], v[16:31]
	ds_read_b64_tr_b16 v[84:85], v0 offset:0x200
	ds_read_b64_tr_b16 v[86:87], v0 offset:0xa00
	v_mfma_f32_32x32x16_bf16 v[16:31], v[8:11], v[88:91], v[16:31]
	ds_read_b64_tr_b16 v[88:89], v0 offset:0x1200
	ds_read_b64_tr_b16 v[90:91], v0 offset:0x1a00
	v_mfma_f32_32x32x16_bf16 v[16:31], v[12:15], v[92:95], v[16:31]
	ds_read_b64_tr_b16 v[92:93], v0 offset:0x2200
	ds_read_b64_tr_b16 v[94:95], v0 offset:0x2a00
	v_mfma_f32_32x32x16_bf16 v[16:31], v[80:83], v[96:99], v[16:31]
	ds_read_b64_tr_b16 v[96:97], v0 offset:0x3200
	ds_read_b64_tr_b16 v[98:99], v0 offset:0x3a00
	s_waitcnt lgkmcnt(0)
	v_mfma_f32_32x32x16_bf16 v[32:47], v[2:5], v[84:87], v[32:47]
	ds_read_b64_tr_b16 v[84:85], v0 offset:0x400
	ds_read_b64_tr_b16 v[86:87], v0 offset:0xc00
	v_mfma_f32_32x32x16_bf16 v[32:47], v[8:11], v[88:91], v[32:47]
	ds_read_b64_tr_b16 v[88:89], v0 offset:0x1400
	ds_read_b64_tr_b16 v[90:91], v0 offset:0x1c00
	v_mfma_f32_32x32x16_bf16 v[32:47], v[12:15], v[92:95], v[32:47]
	ds_read_b64_tr_b16 v[92:93], v0 offset:0x2400
	ds_read_b64_tr_b16 v[94:95], v0 offset:0x2c00
	v_mfma_f32_32x32x16_bf16 v[32:47], v[80:83], v[96:99], v[32:47]
	ds_read_b64_tr_b16 v[96:97], v0 offset:0x3400
	ds_read_b64_tr_b16 v[98:99], v0 offset:0x3c00
	s_waitcnt lgkmcnt(0)
	v_mfma_f32_32x32x16_bf16 v[48:63], v[2:5], v[84:87], v[48:63]
	ds_read_b64_tr_b16 v[84:85], v0 offset:0x600
	ds_read_b64_tr_b16 v[86:87], v0 offset:0xe00
	v_mfma_f32_32x32x16_bf16 v[48:63], v[8:11], v[88:91], v[48:63]
	ds_read_b64_tr_b16 v[88:89], v0 offset:0x1600
	ds_read_b64_tr_b16 v[90:91], v0 offset:0x1e00
	v_mfma_f32_32x32x16_bf16 v[48:63], v[12:15], v[92:95], v[48:63]
	ds_read_b64_tr_b16 v[92:93], v0 offset:0x2600
	ds_read_b64_tr_b16 v[94:95], v0 offset:0x2e00
	v_mfma_f32_32x32x16_bf16 v[48:63], v[80:83], v[96:99], v[48:63]
	ds_read_b64_tr_b16 v[96:97], v0 offset:0x3600
	ds_read_b64_tr_b16 v[98:99], v0 offset:0x3e00
	s_waitcnt lgkmcnt(0)
	v_mfma_f32_32x32x16_bf16 v[64:79], v[2:5], v[84:87], v[64:79]
	v_cmp_nlt_f32_e32 vcc, s27, v7
	v_cmp_ngt_f32_e64 s[0:1], s26, v7
	s_or_b64 s[2:3], vcc, s[0:1]
	v_mfma_f32_32x32x16_bf16 v[64:79], v[8:11], v[88:91], v[64:79]
	v_mfma_f32_32x32x16_bf16 v[64:79], v[12:15], v[92:95], v[64:79]
	v_mfma_f32_32x32x16_bf16 v[64:79], v[80:83], v[96:99], v[64:79]
	s_and_saveexec_b64 s[0:1], s[2:3]
	s_cbranch_execz .LBB0_351
	s_mov_b64 s[2:3], src_shared_base
	s_add_i32 s2, 0, 0x1d000
	s_cmp_lg_u32 s2, -1
	s_cselect_b32 s2, s2, 0
	s_cselect_b32 s3, s3, 0
	v_mov_b32_e32 v2, s2
	v_mov_b32_e32 v3, s3
	flat_store_dword v[2:3], v175 sc0 sc1
	s_waitcnt vmcnt(0)

; #define SBAR() __builtin_amdgcn_sched_barrier(0)
; template <int DK, bool NOMAX> ...
;     ...
;   SBAR();
; #pragma unroll
;   for (int d0 = 0; d0 < NS; ++d0) {
;     if (d0 == 0) { c0 = __builtin_amdgcn_mfma_f32_32x32x16_bf16(kf[0][0], qr[0], f32x16{}, 0, 0, 0); c1 = __builtin_amdgcn_mfma_f32_32x32x16_bf16(kf[0][1], qr[0], f32x16{}, 0, 0, 0); }
;     else { c0 = __builtin_amdgcn_mfma_f32_32x32x16_bf16(kf[d0 & 1][0], qr[d0], c0, 0, 0, 0); c1 = __builtin_amdgcn_mfma_f32_32x32x16_bf16(kf[d0 & 1][1], qr[d0], c1, 0, 0, 0); }
;     if (d0 + 2 < NS) KRD_(d0 & 1, d0 + 2);
;     if constexpr (NOMAX) { }
;     else {
; #pragma unroll
;     for (int r = d0 * RPS; r < (d0 + 1) * RPS; ++r) { p1[r] = __builtin_amdgcn_exp2f(p1[r]); psa += p0[r]; }
;     if (d0 > 0) {
; #pragma unroll
;       for (int r = (d0 - 1) * RPS; r < d0 * RPS; ++r) psb += p1[r]; } }
;     if constexpr (NOMAX) {
;       if (d0 == NS / 4 - 1) { PK4R(p0, 0, pa[0]); PIN(pa[0]); }
;       if (d0 == NS / 2 - 1) { PK4R(p0, 8, pa[1]); PIN(pa[1]); }
;       if (d0 == 3 * NS / 4 - 1) { PK4R(p1, 0, pa[2]); PIN(pa[2]); }
;       if (d0 == NS - 1) { PK4R(p1, 8, pa[3]); PIN(pa[3]); }
;     } else {
;     if (d0 == NS / 2 - 1) { PK4R(p0, 0, pa[0]); PIN(pa[0]); }
;     if (d0 == NS / 2) { PK4R(p0, 8, pa[1]); PIN(pa[1]); }
;     if (d0 == NS - 1) { PK4R(p1, 0, pa[2]); PIN(pa[2]); }
;     }
;     if (d0 == NS - 1) {
;       vl[0] = vtr(vp + v_rd_off(0, 0, 0)); vh[0] = vtr(vp + v_rd_off(0, 0, 1)); vl[1] = vtr(vp + v_rd_off(1, 0, 0)); vh[1] = vtr(vp + v_rd_off(1, 0, 1)); }
;     PIN(p1); PIN(psa); PIN(psb);
;     SBAR();
;   }
; template <int DK, bool NOMAX> ...
;     ...
;   float psa = 0.f, psb = 0.f;
;     ...
;   float ma = 0.f, mb = 0.f, mnC = 0.f;
;   SBAR();
; #pragma unroll
;   for (int i = 0; i < 16; ++i) {
;     if (i + 2 < 16) VRD_((i + 2) % 3, i + 2);
;     if (i == 1) { if (dk) __builtin_amdgcn_global_load_lds((const unsigned*)gk0, lk, 16, 0, 0); }
;     if (i == 3) { if constexpr (DK == 128) { if (dk) __builtin_amdgcn_global_load_lds((const unsigned*)gk1, (lds_up)((lds_cp)lk + 8192), 16, 0, 0); } }
;     if (i == 5) { if (dv) __builtin_amdgcn_global_load_lds((const unsigned*)gv0, lv, 16, 0, 0); }
;     if (i == 7) { if (dv) __builtin_amdgcn_global_load_lds((const unsigned*)gv1, (lds_up)((lds_cp)lv + 8192), 16, 0, 0); }
;     if (i == 12 || i == 13) { const int cb_ = ((i - 12) * 16 + hi * 8) * 2;
.LBB0_420:
	v_add3_u32 v0, 0, v217, v205
	ds_read_b128 v[170:173], v0 offset:49152
	ds_read_b128 v[180:183], v216 offset:57344
	v_mov_b32_e32 v0, v1
	v_mov_b32_e32 v188, v1
	v_mfma_f32_32x32x16_bf16 v[114:129], v[102:105], v[158:161], 0
	v_mfma_f32_32x32x16_bf16 v[98:113], v[98:101], v[158:161], 0
	v_mfma_f32_32x32x16_bf16 v[98:113], v[162:165], v[154:157], v[98:113]
	v_add3_u32 v162, 0, v215, v205
	v_mfma_f32_32x32x16_bf16 v[114:129], v[166:169], v[154:157], v[114:129]
	ds_read_b128 v[166:169], v162 offset:49152
	ds_read_b128 v[184:187], v214 offset:57344
	v_cvt_pk_bf16_f32 v162, v82, v83
	v_cvt_pk_bf16_f32 v163, v84, v85
	v_cvt_pk_bf16_f32 v164, v86, v87
	v_cvt_pk_bf16_f32 v165, v88, v89
	s_nop 0
	v_permlane32_swap_b32_e32 v162, v164
	v_permlane32_swap_b32_e32 v163, v165
	v_add3_u32 v82, 0, v213, v205
	ds_read_b128 v[82:85], v82 offset:49152
	ds_read_b128 v[86:89], v212 offset:57344
	s_waitcnt lgkmcnt(5)
	v_mfma_f32_32x32x16_bf16 v[114:129], v[170:173], v[150:153], v[114:129]
	s_waitcnt lgkmcnt(4)
	v_mfma_f32_32x32x16_bf16 v[98:113], v[180:183], v[150:153], v[98:113]
	s_waitcnt lgkmcnt(3)
	v_mfma_f32_32x32x16_bf16 v[114:129], v[166:169], v[146:149], v[114:129]
	v_add3_u32 v166, 0, v211, v205
	ds_read_b128 v[166:169], v166 offset:49152
	ds_read_b128 v[170:173], v210 offset:57344
	v_cvt_pk_bf16_f32 v90, v90, v91
	v_cvt_pk_bf16_f32 v91, v92, v93
	v_cvt_pk_bf16_f32 v92, v94, v95
	v_cvt_pk_bf16_f32 v93, v96, v97
	s_nop 0
	v_permlane32_swap_b32_e32 v90, v92
	v_permlane32_swap_b32_e32 v91, v93
	s_waitcnt lgkmcnt(4)
	v_mfma_f32_32x32x16_bf16 v[98:113], v[184:187], v[146:149], v[98:113]
	s_waitcnt lgkmcnt(3)
	v_mfma_f32_32x32x16_bf16 v[114:129], v[82:85], v[142:145], v[114:129]
	v_add3_u32 v82, 0, v209, v205
	ds_read_b128 v[82:85], v82 offset:49152
	ds_read_b128 v[94:97], v208 offset:57344
	s_waitcnt lgkmcnt(4)
	v_mfma_f32_32x32x16_bf16 v[98:113], v[86:89], v[142:145], v[98:113]
	v_add3_u32 v86, 0, v207, v205
	s_waitcnt lgkmcnt(3)
	v_mfma_f32_32x32x16_bf16 v[114:129], v[166:169], v[138:141], v[114:129]
	s_waitcnt lgkmcnt(2)
	v_mfma_f32_32x32x16_bf16 v[98:113], v[170:173], v[138:141], v[98:113]
	ds_read_b128 v[166:169], v86 offset:49152
	ds_read_b128 v[170:173], v206 offset:57344
	v_cvt_pk_bf16_f32 v86, v66, v67
	v_cvt_pk_bf16_f32 v87, v68, v69
	v_cvt_pk_bf16_f32 v88, v70, v71
	v_cvt_pk_bf16_f32 v89, v72, v73
	s_nop 0
	v_permlane32_swap_b32_e32 v86, v88
	v_permlane32_swap_b32_e32 v87, v89
	s_waitcnt lgkmcnt(3)
	v_mfma_f32_32x32x16_bf16 v[114:129], v[82:85], v[130:133], v[114:129]
	s_waitcnt lgkmcnt(2)
	v_mfma_f32_32x32x16_bf16 v[98:113], v[94:97], v[130:133], v[98:113]
	v_cvt_pk_bf16_f32 v82, v74, v75
	v_cvt_pk_bf16_f32 v83, v76, v77
	v_cvt_pk_bf16_f32 v84, v78, v79
	v_cvt_pk_bf16_f32 v85, v80, v81
	s_waitcnt lgkmcnt(1)
	v_mfma_f32_32x32x16_bf16 v[114:129], v[166:169], v[134:137], v[114:129]
	v_permlane32_swap_b32_e32 v82, v84
	v_permlane32_swap_b32_e32 v83, v85
	s_waitcnt vmcnt(0) lgkmcnt(0)
	s_barrier
	ds_read_b64_tr_b16 v[94:95], v204
	ds_read_b64_tr_b16 v[96:97], v204 offset:2048
	ds_read_b64_tr_b16 v[166:167], v204 offset:512
	ds_read_b64_tr_b16 v[168:169], v204 offset:2560
	s_waitcnt lgkmcnt(4)
	v_mfma_f32_32x32x16_bf16 v[98:113], v[170:173], v[134:137], v[98:113]
	ds_read_b64_tr_b16 v[66:67], v204 offset:1024
	ds_read_b64_tr_b16 v[68:69], v204 offset:3072
	s_waitcnt lgkmcnt(4)
	v_mfma_f32_32x32x16_bf16 v[50:65], v[162:165], v[94:97], v[50:65]
	s_nop 0
	v_exp_f32_e32 v114, v114
	s_nop 5
	v_exp_f32_e32 v98, v98
	v_mov_b32_e32 v0, v1
	v_mov_b32_e32 v74, v1
	ds_read_b64_tr_b16 v[70:71], v204 offset:1536
	ds_read_b64_tr_b16 v[72:73], v204 offset:3584
	s_waitcnt lgkmcnt(4)
	v_mfma_f32_32x32x16_bf16 v[34:49], v[162:165], v[166:169], v[34:49]
	v_exp_f32_e32 v115, v115
	v_exp_f32_e32 v99, v99
	v_add_f32_e32 v78, v98, v74
	v_add_f32_e32 v0, v114, v0
	ds_read_b64_tr_b16 v[74:75], v204 offset:4096
	ds_read_b64_tr_b16 v[76:77], v204 offset:6144
	s_waitcnt lgkmcnt(4)
	v_mfma_f32_32x32x16_bf16 v[18:33], v[162:165], v[66:69], v[18:33]
	v_exp_f32_e32 v116, v116
	v_exp_f32_e32 v100, v100
	v_add_f32_e32 v78, v99, v78
	v_add_f32_e32 v0, v115, v0
	ds_read_b64_tr_b16 v[66:67], v204 offset:4608
	ds_read_b64_tr_b16 v[68:69], v204 offset:6656
	s_waitcnt lgkmcnt(4)
	v_mfma_f32_32x32x16_bf16 v[2:17], v[162:165], v[70:73], v[2:17]
	v_exp_f32_e32 v117, v117
	v_exp_f32_e32 v101, v101
	v_add_f32_e32 v78, v100, v78
	v_add_f32_e32 v0, v116, v0
	ds_read_b64_tr_b16 v[70:71], v204 offset:5120
	ds_read_b64_tr_b16 v[72:73], v204 offset:7168
	s_waitcnt lgkmcnt(4)
	v_mfma_f32_32x32x16_bf16 v[50:65], v[90:93], v[74:77], v[50:65]
	v_exp_f32_e32 v118, v118
	v_exp_f32_e32 v102, v102
	v_add_f32_e32 v78, v101, v78
	v_add_f32_e32 v0, v117, v0
	ds_read_b64_tr_b16 v[74:75], v204 offset:5632
	ds_read_b64_tr_b16 v[76:77], v204 offset:7680
	s_waitcnt lgkmcnt(4)
	v_mfma_f32_32x32x16_bf16 v[34:49], v[90:93], v[66:69], v[34:49]
	v_exp_f32_e32 v119, v119
	v_exp_f32_e32 v103, v103
	v_add_f32_e32 v78, v102, v78
	v_add_f32_e32 v0, v118, v0
	ds_read_b64_tr_b16 v[66:67], v204 offset:8192
	ds_read_b64_tr_b16 v[68:69], v204 offset:10240
	s_waitcnt lgkmcnt(4)
	v_mfma_f32_32x32x16_bf16 v[18:33], v[90:93], v[70:73], v[18:33]
	v_exp_f32_e32 v120, v120
	v_exp_f32_e32 v104, v104
	v_add_f32_e32 v78, v103, v78
	v_add_f32_e32 v0, v119, v0
	ds_read_b64_tr_b16 v[70:71], v204 offset:8704
	ds_read_b64_tr_b16 v[72:73], v204 offset:10752
	s_waitcnt lgkmcnt(4)
	v_mfma_f32_32x32x16_bf16 v[2:17], v[90:93], v[74:77], v[2:17]
	v_exp_f32_e32 v121, v121
	v_exp_f32_e32 v105, v105
	v_add_f32_e32 v78, v104, v78
	v_add_f32_e32 v0, v120, v0
	ds_read_b64_tr_b16 v[74:75], v204 offset:9216
	ds_read_b64_tr_b16 v[76:77], v204 offset:11264
	s_waitcnt lgkmcnt(4)
; #define SBAR() __builtin_amdgcn_sched_barrier(0)
; template <int DK, bool NOMAX> ...
;     ...
;     SBAR();
;   }
;     ...
;   if constexpr (NOMAX) { float ps = (psa + c0[15]) + (psb + c1[15]);
;     { auto rr = __builtin_amdgcn_permlane32_swap(__float_as_uint(ps), __float_as_uint(ps), false, false);
;       ps = __uint_as_float(rr[0]) + __uint_as_float(rr[1]); }
;     l_reg = l_reg * alpha + ps; }
; template <int DK, int LDK, bool BIAS, bool NOMAX> ...
;     ...
;   STEPT(pB0, pB1, pA0, pA1, alA, alB, NT - 1);
;   if constexpr (NOMAX) { PK4R(pB0, 0, pa[0]); PK4R(pB0, 8, pa[1]); PK4R(pB1, 0, pa[2]); PK4R(pB1, 8, pa[3]); }
;   else finishSM<false>(pB0, pB1, alB, l_reg, pa[0], pa[1], pa[2], pa[3]);
;   SBAR();
;   pv_d0(o, vb0 + sp, pa[0], pa[1], pa[2], pa[3]);
;   l_out = l_reg;
	v_mfma_f32_32x32x16_bf16 v[50:65], v[86:89], v[66:69], v[50:65]
	v_exp_f32_e32 v122, v122
	v_exp_f32_e32 v106, v106
	v_add_f32_e32 v78, v105, v78
	v_add_f32_e32 v0, v121, v0
	ds_read_b64_tr_b16 v[66:67], v204 offset:9728
	ds_read_b64_tr_b16 v[68:69], v204 offset:11776
	s_waitcnt lgkmcnt(4)
	v_mfma_f32_32x32x16_bf16 v[34:49], v[86:89], v[70:73], v[34:49]
	v_exp_f32_e32 v123, v123
	v_exp_f32_e32 v107, v107
	v_add_f32_e32 v78, v106, v78
	v_add_f32_e32 v0, v122, v0
	ds_read_b64_tr_b16 v[70:71], v204 offset:12288
	ds_read_b64_tr_b16 v[72:73], v204 offset:14336
	s_waitcnt lgkmcnt(4)
	v_mfma_f32_32x32x16_bf16 v[18:33], v[86:89], v[74:77], v[18:33]
	v_exp_f32_e32 v124, v124
	v_exp_f32_e32 v108, v108
	v_add_f32_e32 v78, v107, v78
	v_add_f32_e32 v0, v123, v0
	ds_read_b64_tr_b16 v[74:75], v204 offset:12800
	ds_read_b64_tr_b16 v[76:77], v204 offset:14848
	s_waitcnt lgkmcnt(4)
	v_mfma_f32_32x32x16_bf16 v[2:17], v[86:89], v[66:69], v[2:17]
	v_exp_f32_e32 v125, v125
	v_exp_f32_e32 v109, v109
	v_add_f32_e32 v78, v108, v78
	v_add_f32_e32 v0, v124, v0
	ds_read_b64_tr_b16 v[66:67], v204 offset:13312
	ds_read_b64_tr_b16 v[68:69], v204 offset:15360
	s_waitcnt lgkmcnt(4)
	v_mfma_f32_32x32x16_bf16 v[50:65], v[82:85], v[70:73], v[50:65]
	v_exp_f32_e32 v126, v126
	v_exp_f32_e32 v110, v110
	v_add_f32_e32 v78, v109, v78
	v_add_f32_e32 v0, v125, v0
	ds_read_b64_tr_b16 v[70:71], v204 offset:13824
	ds_read_b64_tr_b16 v[72:73], v204 offset:15872
	s_waitcnt lgkmcnt(4)
	v_mfma_f32_32x32x16_bf16 v[34:49], v[82:85], v[74:77], v[34:49]
	v_exp_f32_e32 v127, v127
	v_exp_f32_e32 v111, v111
	v_add_f32_e32 v74, v110, v78
	v_add_f32_e32 v0, v126, v0
	s_waitcnt lgkmcnt(2)
	v_mfma_f32_32x32x16_bf16 v[18:33], v[82:85], v[66:69], v[18:33]
	v_exp_f32_e32 v128, v128
	v_exp_f32_e32 v112, v112
	v_add_f32_e32 v66, v111, v74
	v_add_f32_e32 v0, v127, v0
	s_waitcnt lgkmcnt(0)
	v_mfma_f32_32x32x16_bf16 v[2:17], v[82:85], v[70:73], v[2:17]
	v_exp_f32_e32 v129, v129
	v_exp_f32_e32 v113, v113
	v_add_f32_e32 v67, v112, v66
	v_add_f32_e32 v66, v128, v0
	s_nop 0
	v_mov_b32_e32 v68, v129
	v_mov_b32_e32 v69, v113
	v_pk_add_f32 v[66:67], v[68:69], v[66:67]
	s_waitcnt vmcnt(0) lgkmcnt(0)
	s_nop 0
	v_pk_add_f32 v[66:67], v[66:67], v[66:67] op_sel:[0,1] op_sel_hi:[1,0]
	s_nop 0
	v_mov_b32_e32 v0, v66
	s_nop 1
	v_permlane32_swap_b32_e32 v66, v0
	v_add_f32_e32 v0, v66, v0
	v_add_f32_e32 v71, v203, v0
	v_cvt_pk_bf16_f32 v66, v114, v115
	v_cvt_pk_bf16_f32 v67, v116, v117
	v_cvt_pk_bf16_f32 v68, v118, v119
	v_cvt_pk_bf16_f32 v69, v120, v121
	v_cvt_pk_bf16_f32 v72, v122, v123
	v_cvt_pk_bf16_f32 v73, v124, v125
	v_cvt_pk_bf16_f32 v74, v126, v127
	v_cvt_pk_bf16_f32 v75, v128, v129
	v_cvt_pk_bf16_f32 v76, v98, v99
	v_cvt_pk_bf16_f32 v77, v100, v101
	v_cvt_pk_bf16_f32 v78, v102, v103
	v_cvt_pk_bf16_f32 v79, v104, v105
	v_cvt_pk_bf16_f32 v80, v106, v107
	v_cvt_pk_bf16_f32 v81, v108, v109
	v_cvt_pk_bf16_f32 v82, v110, v111
	v_cvt_pk_bf16_f32 v83, v112, v113
	s_nop 0
	v_permlane32_swap_b32_e32 v66, v68
	v_permlane32_swap_b32_e32 v67, v69
	v_permlane32_swap_b32_e32 v72, v74
	v_permlane32_swap_b32_e32 v73, v75
	v_permlane32_swap_b32_e32 v76, v78
	v_permlane32_swap_b32_e32 v77, v79
	v_permlane32_swap_b32_e32 v80, v82
	v_permlane32_swap_b32_e32 v81, v83
	s_cmp_lg_u32 s41, -1
	s_cselect_b32 s0, s41, 0
	s_addk_i32 s0, 0x4000
	v_add_u32_e32 v0, s0, v202
	ds_read_b64_tr_b16 v[84:85], v0 offset:0
	ds_read_b64_tr_b16 v[86:87], v0 offset:0x800
	ds_read_b64_tr_b16 v[88:89], v0 offset:0x1000
	ds_read_b64_tr_b16 v[90:91], v0 offset:0x1800
	ds_read_b64_tr_b16 v[92:93], v0 offset:0x2000
	ds_read_b64_tr_b16 v[94:95], v0 offset:0x2800
	ds_read_b64_tr_b16 v[96:97], v0 offset:0x3000
	ds_read_b64_tr_b16 v[98:99], v0 offset:0x3800
	s_waitcnt lgkmcnt(0)
	s_nop 0
	v_mfma_f32_32x32x16_bf16 v[50:65], v[66:69], v[84:87], v[50:65]
	ds_read_b64_tr_b16 v[84:85], v0 offset:0x200
	ds_read_b64_tr_b16 v[86:87], v0 offset:0xa00
	v_mfma_f32_32x32x16_bf16 v[50:65], v[72:75], v[88:91], v[50:65]
	ds_read_b64_tr_b16 v[88:89], v0 offset:0x1200
	ds_read_b64_tr_b16 v[90:91], v0 offset:0x1a00
	v_mfma_f32_32x32x16_bf16 v[50:65], v[76:79], v[92:95], v[50:65]
	ds_read_b64_tr_b16 v[92:93], v0 offset:0x2200
	ds_read_b64_tr_b16 v[94:95], v0 offset:0x2a00
	v_mfma_f32_32x32x16_bf16 v[50:65], v[80:83], v[96:99], v[50:65]
	ds_read_b64_tr_b16 v[96:97], v0 offset:0x3200
	ds_read_b64_tr_b16 v[98:99], v0 offset:0x3a00
	s_waitcnt lgkmcnt(0)
	v_mfma_f32_32x32x16_bf16 v[34:49], v[66:69], v[84:87], v[34:49]
	ds_read_b64_tr_b16 v[84:85], v0 offset:0x400
	ds_read_b64_tr_b16 v[86:87], v0 offset:0xc00
	v_mfma_f32_32x32x16_bf16 v[34:49], v[72:75], v[88:91], v[34:49]
	ds_read_b64_tr_b16 v[88:89], v0 offset:0x1400
	ds_read_b64_tr_b16 v[90:91], v0 offset:0x1c00
	v_mfma_f32_32x32x16_bf16 v[34:49], v[76:79], v[92:95], v[34:49]
	ds_read_b64_tr_b16 v[92:93], v0 offset:0x2400
	ds_read_b64_tr_b16 v[94:95], v0 offset:0x2c00
	v_mfma_f32_32x32x16_bf16 v[34:49], v[80:83], v[96:99], v[34:49]
	ds_read_b64_tr_b16 v[96:97], v0 offset:0x3400
	ds_read_b64_tr_b16 v[98:99], v0 offset:0x3c00
	s_waitcnt lgkmcnt(0)
	v_mfma_f32_32x32x16_bf16 v[18:33], v[66:69], v[84:87], v[18:33]
	ds_read_b64_tr_b16 v[84:85], v0 offset:0x600
	ds_read_b64_tr_b16 v[86:87], v0 offset:0xe00
	v_mfma_f32_32x32x16_bf16 v[18:33], v[72:75], v[88:91], v[18:33]
	ds_read_b64_tr_b16 v[88:89], v0 offset:0x1600
	ds_read_b64_tr_b16 v[90:91], v0 offset:0x1e00
	v_mfma_f32_32x32x16_bf16 v[18:33], v[76:79], v[92:95], v[18:33]
	ds_read_b64_tr_b16 v[92:93], v0 offset:0x2600
	ds_read_b64_tr_b16 v[94:95], v0 offset:0x2e00
	v_mfma_f32_32x32x16_bf16 v[18:33], v[80:83], v[96:99], v[18:33]
	ds_read_b64_tr_b16 v[96:97], v0 offset:0x3600
	ds_read_b64_tr_b16 v[98:99], v0 offset:0x3e00
	s_waitcnt lgkmcnt(0)
	v_mfma_f32_32x32x16_bf16 v[2:17], v[66:69], v[84:87], v[2:17]
	v_cmp_nlt_f32_e32 vcc, s27, v71
	v_cmp_ngt_f32_e64 s[0:1], s26, v71
	s_or_b64 s[2:3], vcc, s[0:1]
	v_mfma_f32_32x32x16_bf16 v[2:17], v[72:75], v[88:91], v[2:17]
	v_mfma_f32_32x32x16_bf16 v[2:17], v[76:79], v[92:95], v[2:17]
	v_mfma_f32_32x32x16_bf16 v[2:17], v[80:83], v[96:99], v[2:17]
	s_and_saveexec_b64 s[0:1], s[2:3]
	s_cbranch_execz .LBB0_422
	s_mov_b64 s[2:3], src_shared_base
	s_add_i32 s2, 0, 0x1d000
	s_cmp_lg_u32 s2, -1
	s_cselect_b32 s2, s2, 0
	s_cselect_b32 s3, s3, 0
	v_mov_b32_e32 v66, s2
	v_mov_b32_e32 v67, s3
	flat_store_dword v[66:67], v175 sc0 sc1
	s_waitcnt vmcnt(0)

; #define SBAR() __builtin_amdgcn_sched_barrier(0)
; template <int DK, bool NOMAX> ...
;     ...
;   SBAR();
; #pragma unroll
;   for (int d0 = 0; d0 < NS; ++d0) {
;     if (d0 == 0) { c0 = __builtin_amdgcn_mfma_f32_32x32x16_bf16(kf[0][0], qr[0], f32x16{}, 0, 0, 0); c1 = __builtin_amdgcn_mfma_f32_32x32x16_bf16(kf[0][1], qr[0], f32x16{}, 0, 0, 0); }
;     else { c0 = __builtin_amdgcn_mfma_f32_32x32x16_bf16(kf[d0 & 1][0], qr[d0], c0, 0, 0, 0); c1 = __builtin_amdgcn_mfma_f32_32x32x16_bf16(kf[d0 & 1][1], qr[d0], c1, 0, 0, 0); }
;     if (d0 + 2 < NS) KRD_(d0 & 1, d0 + 2);
;     if constexpr (NOMAX) { }
;     else {
; #pragma unroll
;     for (int r = d0 * RPS; r < (d0 + 1) * RPS; ++r) { p1[r] = __builtin_amdgcn_exp2f(p1[r]); psa += p0[r]; }
;     if (d0 > 0) {
; #pragma unroll
;       for (int r = (d0 - 1) * RPS; r < d0 * RPS; ++r) psb += p1[r]; } }
;     if constexpr (NOMAX) {
;       if (d0 == NS / 4 - 1) { PK4R(p0, 0, pa[0]); PIN(pa[0]); }
;       if (d0 == NS / 2 - 1) { PK4R(p0, 8, pa[1]); PIN(pa[1]); }
;       if (d0 == 3 * NS / 4 - 1) { PK4R(p1, 0, pa[2]); PIN(pa[2]); }
;       if (d0 == NS - 1) { PK4R(p1, 8, pa[3]); PIN(pa[3]); }
;     } else {
;     if (d0 == NS / 2 - 1) { PK4R(p0, 0, pa[0]); PIN(pa[0]); }
;     if (d0 == NS / 2) { PK4R(p0, 8, pa[1]); PIN(pa[1]); }
;     if (d0 == NS - 1) { PK4R(p1, 0, pa[2]); PIN(pa[2]); }
;     }
;     if (d0 == NS - 1) {
;       vl[0] = vtr(vp + v_rd_off(0, 0, 0)); vh[0] = vtr(vp + v_rd_off(0, 0, 1)); vl[1] = vtr(vp + v_rd_off(1, 0, 0)); vh[1] = vtr(vp + v_rd_off(1, 0, 1)); }
;     PIN(p1); PIN(psa); PIN(psb);
;     SBAR();
;   }
; template <int DK, bool NOMAX> ...
;     ...
;   float psa = 0.f, psb = 0.f;
;     ...
;   float ma = 0.f, mb = 0.f, mnC = 0.f;
;   SBAR();
; #pragma unroll
;   for (int i = 0; i < 16; ++i) {
;     if (i + 2 < 16) VRD_((i + 2) % 3, i + 2);
;     if (i == 1) { if (dk) __builtin_amdgcn_global_load_lds((const unsigned*)gk0, lk, 16, 0, 0); }
;     if (i == 3) { if constexpr (DK == 128) { if (dk) __builtin_amdgcn_global_load_lds((const unsigned*)gk1, (lds_up)((lds_cp)lk + 8192), 16, 0, 0); } }
;     if (i == 5) { if (dv) __builtin_amdgcn_global_load_lds((const unsigned*)gv0, lv, 16, 0, 0); }
;     if (i == 7) { if (dv) __builtin_amdgcn_global_load_lds((const unsigned*)gv1, (lds_up)((lds_cp)lv + 8192), 16, 0, 0); }
;     if (i == 12 || i == 13) { const int cb_ = ((i - 12) * 16 + hi * 8) * 2;
.LBB0_480:
	v_add3_u32 v0, 0, v217, v205
	ds_read_b128 v[170:173], v0 offset:49152
	ds_read_b128 v[180:183], v216 offset:57344
	v_mov_b32_e32 v0, v1
	v_mov_b32_e32 v188, v1
	v_mfma_f32_32x32x16_bf16 v[114:129], v[102:105], v[158:161], 0
	v_mfma_f32_32x32x16_bf16 v[98:113], v[98:101], v[158:161], 0
	v_mfma_f32_32x32x16_bf16 v[98:113], v[162:165], v[154:157], v[98:113]
	v_add3_u32 v162, 0, v215, v205
	v_mfma_f32_32x32x16_bf16 v[114:129], v[166:169], v[154:157], v[114:129]
	ds_read_b128 v[166:169], v162 offset:49152
	ds_read_b128 v[184:187], v214 offset:57344
	v_cvt_pk_bf16_f32 v162, v82, v83
	v_cvt_pk_bf16_f32 v163, v84, v85
	v_cvt_pk_bf16_f32 v164, v86, v87
	v_cvt_pk_bf16_f32 v165, v88, v89
	s_nop 0
	v_permlane32_swap_b32_e32 v162, v164
	v_permlane32_swap_b32_e32 v163, v165
	v_add3_u32 v82, 0, v213, v205
	ds_read_b128 v[82:85], v82 offset:49152
	ds_read_b128 v[86:89], v212 offset:57344
	s_waitcnt lgkmcnt(5)
	v_mfma_f32_32x32x16_bf16 v[114:129], v[170:173], v[150:153], v[114:129]
	s_waitcnt lgkmcnt(4)
	v_mfma_f32_32x32x16_bf16 v[98:113], v[180:183], v[150:153], v[98:113]
	s_waitcnt lgkmcnt(3)
	v_mfma_f32_32x32x16_bf16 v[114:129], v[166:169], v[146:149], v[114:129]
	v_add3_u32 v166, 0, v211, v205
	ds_read_b128 v[166:169], v166 offset:49152
	ds_read_b128 v[170:173], v210 offset:57344
	v_cvt_pk_bf16_f32 v90, v90, v91
	v_cvt_pk_bf16_f32 v91, v92, v93
	v_cvt_pk_bf16_f32 v92, v94, v95
	v_cvt_pk_bf16_f32 v93, v96, v97
	s_nop 0
	v_permlane32_swap_b32_e32 v90, v92
	v_permlane32_swap_b32_e32 v91, v93
	s_waitcnt lgkmcnt(4)
	v_mfma_f32_32x32x16_bf16 v[98:113], v[184:187], v[146:149], v[98:113]
	s_waitcnt lgkmcnt(3)
	v_mfma_f32_32x32x16_bf16 v[114:129], v[82:85], v[142:145], v[114:129]
	v_add3_u32 v82, 0, v209, v205
	ds_read_b128 v[82:85], v82 offset:49152
	ds_read_b128 v[94:97], v208 offset:57344
	s_waitcnt lgkmcnt(4)
	v_mfma_f32_32x32x16_bf16 v[98:113], v[86:89], v[142:145], v[98:113]
	v_add3_u32 v86, 0, v207, v205
	s_waitcnt lgkmcnt(3)
	v_mfma_f32_32x32x16_bf16 v[114:129], v[166:169], v[138:141], v[114:129]
	s_waitcnt lgkmcnt(2)
	v_mfma_f32_32x32x16_bf16 v[98:113], v[170:173], v[138:141], v[98:113]
	ds_read_b128 v[166:169], v86 offset:49152
	ds_read_b128 v[170:173], v206 offset:57344
	v_cvt_pk_bf16_f32 v86, v66, v67
	v_cvt_pk_bf16_f32 v87, v68, v69
	v_cvt_pk_bf16_f32 v88, v70, v71
	v_cvt_pk_bf16_f32 v89, v72, v73
	s_nop 0
	v_permlane32_swap_b32_e32 v86, v88
	v_permlane32_swap_b32_e32 v87, v89
	s_waitcnt lgkmcnt(3)
	v_mfma_f32_32x32x16_bf16 v[114:129], v[82:85], v[130:133], v[114:129]
	s_waitcnt lgkmcnt(2)
	v_mfma_f32_32x32x16_bf16 v[98:113], v[94:97], v[130:133], v[98:113]
	v_cvt_pk_bf16_f32 v82, v74, v75
	v_cvt_pk_bf16_f32 v83, v76, v77
	v_cvt_pk_bf16_f32 v84, v78, v79
	v_cvt_pk_bf16_f32 v85, v80, v81
	s_waitcnt lgkmcnt(1)
	v_mfma_f32_32x32x16_bf16 v[114:129], v[166:169], v[134:137], v[114:129]
	v_permlane32_swap_b32_e32 v82, v84
	v_permlane32_swap_b32_e32 v83, v85
	s_waitcnt vmcnt(0) lgkmcnt(0)
	s_barrier
	ds_read_b64_tr_b16 v[94:95], v204 offset:32768
	ds_read_b64_tr_b16 v[96:97], v204 offset:34816
	ds_read_b64_tr_b16 v[166:167], v204 offset:33280
	ds_read_b64_tr_b16 v[168:169], v204 offset:35328
	s_waitcnt lgkmcnt(4)
	v_mfma_f32_32x32x16_bf16 v[98:113], v[170:173], v[134:137], v[98:113]
	ds_read_b64_tr_b16 v[66:67], v204 offset:33792
	ds_read_b64_tr_b16 v[68:69], v204 offset:35840
	s_waitcnt lgkmcnt(4)
	v_mfma_f32_32x32x16_bf16 v[50:65], v[162:165], v[94:97], v[50:65]
	s_nop 0
	v_exp_f32_e32 v114, v114
	s_nop 5
	v_exp_f32_e32 v98, v98
	v_mov_b32_e32 v0, v1
	v_mov_b32_e32 v74, v1
	ds_read_b64_tr_b16 v[70:71], v204 offset:34304
	ds_read_b64_tr_b16 v[72:73], v204 offset:36352
	s_waitcnt lgkmcnt(4)
	v_mfma_f32_32x32x16_bf16 v[34:49], v[162:165], v[166:169], v[34:49]
	v_exp_f32_e32 v115, v115
	v_exp_f32_e32 v99, v99
	v_add_f32_e32 v78, v98, v74
	v_add_f32_e32 v0, v114, v0
	ds_read_b64_tr_b16 v[74:75], v204 offset:36864
	ds_read_b64_tr_b16 v[76:77], v204 offset:38912
	s_waitcnt lgkmcnt(4)
	v_mfma_f32_32x32x16_bf16 v[18:33], v[162:165], v[66:69], v[18:33]
	v_exp_f32_e32 v116, v116
	v_exp_f32_e32 v100, v100
	v_add_f32_e32 v78, v99, v78
	v_add_f32_e32 v0, v115, v0
	ds_read_b64_tr_b16 v[66:67], v204 offset:37376
	ds_read_b64_tr_b16 v[68:69], v204 offset:39424
	s_waitcnt lgkmcnt(4)
	v_mfma_f32_32x32x16_bf16 v[2:17], v[162:165], v[70:73], v[2:17]
	v_exp_f32_e32 v117, v117
	v_exp_f32_e32 v101, v101
	v_add_f32_e32 v78, v100, v78
	v_add_f32_e32 v0, v116, v0
	ds_read_b64_tr_b16 v[70:71], v204 offset:37888
	ds_read_b64_tr_b16 v[72:73], v204 offset:39936
	s_waitcnt lgkmcnt(4)
	v_mfma_f32_32x32x16_bf16 v[50:65], v[90:93], v[74:77], v[50:65]
	v_exp_f32_e32 v118, v118
	v_exp_f32_e32 v102, v102
	v_add_f32_e32 v78, v101, v78
	v_add_f32_e32 v0, v117, v0
	ds_read_b64_tr_b16 v[74:75], v204 offset:38400
	ds_read_b64_tr_b16 v[76:77], v204 offset:40448
	s_waitcnt lgkmcnt(4)
	v_mfma_f32_32x32x16_bf16 v[34:49], v[90:93], v[66:69], v[34:49]
	v_exp_f32_e32 v119, v119
	v_exp_f32_e32 v103, v103
	v_add_f32_e32 v78, v102, v78
	v_add_f32_e32 v0, v118, v0
	ds_read_b64_tr_b16 v[66:67], v204 offset:40960
	ds_read_b64_tr_b16 v[68:69], v204 offset:43008
	s_waitcnt lgkmcnt(4)
	v_mfma_f32_32x32x16_bf16 v[18:33], v[90:93], v[70:73], v[18:33]
	v_exp_f32_e32 v120, v120
	v_exp_f32_e32 v104, v104
	v_add_f32_e32 v78, v103, v78
	v_add_f32_e32 v0, v119, v0
	ds_read_b64_tr_b16 v[70:71], v204 offset:41472
	ds_read_b64_tr_b16 v[72:73], v204 offset:43520
	s_waitcnt lgkmcnt(4)
	v_mfma_f32_32x32x16_bf16 v[2:17], v[90:93], v[74:77], v[2:17]
	v_exp_f32_e32 v121, v121
	v_exp_f32_e32 v105, v105
	v_add_f32_e32 v78, v104, v78
	v_add_f32_e32 v0, v120, v0
	ds_read_b64_tr_b16 v[74:75], v204 offset:41984
	ds_read_b64_tr_b16 v[76:77], v204 offset:44032
	s_waitcnt lgkmcnt(4)
; #define SBAR() __builtin_amdgcn_sched_barrier(0)
; template <int DK, bool NOMAX> ...
;     ...
;     SBAR();
;   }
;     ...
;   if constexpr (NOMAX) { float ps = (psa + c0[15]) + (psb + c1[15]);
;     { auto rr = __builtin_amdgcn_permlane32_swap(__float_as_uint(ps), __float_as_uint(ps), false, false);
;       ps = __uint_as_float(rr[0]) + __uint_as_float(rr[1]); }
;     l_reg = l_reg * alpha + ps; }
; template <int DK, int LDK, bool BIAS, bool NOMAX> ...
;     ...
;   STEPT(pB0, pB1, pA0, pA1, alA, alB, NT - 1);
;   if constexpr (NOMAX) { PK4R(pB0, 0, pa[0]); PK4R(pB0, 8, pa[1]); PK4R(pB1, 0, pa[2]); PK4R(pB1, 8, pa[3]); }
;   else finishSM<false>(pB0, pB1, alB, l_reg, pa[0], pa[1], pa[2], pa[3]);
;   SBAR();
;   pv_d0(o, vb0 + sp, pa[0], pa[1], pa[2], pa[3]);
;   l_out = l_reg;
	v_mfma_f32_32x32x16_bf16 v[50:65], v[86:89], v[66:69], v[50:65]
	v_exp_f32_e32 v122, v122
	v_exp_f32_e32 v106, v106
	v_add_f32_e32 v78, v105, v78
	v_add_f32_e32 v0, v121, v0
	ds_read_b64_tr_b16 v[66:67], v204 offset:42496
	ds_read_b64_tr_b16 v[68:69], v204 offset:44544
	s_waitcnt lgkmcnt(4)
	v_mfma_f32_32x32x16_bf16 v[34:49], v[86:89], v[70:73], v[34:49]
	v_exp_f32_e32 v123, v123
	v_exp_f32_e32 v107, v107
	v_add_f32_e32 v78, v106, v78
	v_add_f32_e32 v0, v122, v0
	ds_read_b64_tr_b16 v[70:71], v204 offset:45056
	ds_read_b64_tr_b16 v[72:73], v204 offset:47104
	s_waitcnt lgkmcnt(4)
	v_mfma_f32_32x32x16_bf16 v[18:33], v[86:89], v[74:77], v[18:33]
	v_exp_f32_e32 v124, v124
	v_exp_f32_e32 v108, v108
	v_add_f32_e32 v78, v107, v78
	v_add_f32_e32 v0, v123, v0
	ds_read_b64_tr_b16 v[74:75], v204 offset:45568
	ds_read_b64_tr_b16 v[76:77], v204 offset:47616
	s_waitcnt lgkmcnt(4)
	v_mfma_f32_32x32x16_bf16 v[2:17], v[86:89], v[66:69], v[2:17]
	v_exp_f32_e32 v125, v125
	v_exp_f32_e32 v109, v109
	v_add_f32_e32 v78, v108, v78
	v_add_f32_e32 v0, v124, v0
	ds_read_b64_tr_b16 v[66:67], v204 offset:46080
	ds_read_b64_tr_b16 v[68:69], v204 offset:48128
	s_waitcnt lgkmcnt(4)
	v_mfma_f32_32x32x16_bf16 v[50:65], v[82:85], v[70:73], v[50:65]
	v_exp_f32_e32 v126, v126
	v_exp_f32_e32 v110, v110
	v_add_f32_e32 v78, v109, v78
	v_add_f32_e32 v0, v125, v0
	ds_read_b64_tr_b16 v[70:71], v204 offset:46592
	ds_read_b64_tr_b16 v[72:73], v204 offset:48640
	s_waitcnt lgkmcnt(4)
	v_mfma_f32_32x32x16_bf16 v[34:49], v[82:85], v[74:77], v[34:49]
	v_exp_f32_e32 v127, v127
	v_exp_f32_e32 v111, v111
	v_add_f32_e32 v74, v110, v78
	v_add_f32_e32 v0, v126, v0
	s_waitcnt lgkmcnt(2)
	v_mfma_f32_32x32x16_bf16 v[18:33], v[82:85], v[66:69], v[18:33]
	v_exp_f32_e32 v128, v128
	v_exp_f32_e32 v112, v112
	v_add_f32_e32 v66, v111, v74
	v_add_f32_e32 v0, v127, v0
	s_waitcnt lgkmcnt(0)
	v_mfma_f32_32x32x16_bf16 v[2:17], v[82:85], v[70:73], v[2:17]
	v_exp_f32_e32 v129, v129
	v_exp_f32_e32 v113, v113
	v_add_f32_e32 v67, v112, v66
	v_add_f32_e32 v66, v128, v0
	s_nop 0
	v_mov_b32_e32 v68, v129
	v_mov_b32_e32 v69, v113
	v_pk_add_f32 v[66:67], v[68:69], v[66:67]
	s_waitcnt vmcnt(0) lgkmcnt(0)
	s_cmp_lg_u32 s41, -1
	v_pk_add_f32 v[66:67], v[66:67], v[66:67] op_sel:[0,1] op_sel_hi:[1,0]
	s_cselect_b32 s0, s41, 0
	v_mov_b32_e32 v0, v66
	s_nop 1
	v_permlane32_swap_b32_e32 v66, v0
	v_add_f32_e32 v0, v66, v0
	v_add_f32_e32 v71, v203, v0
	v_cvt_pk_bf16_f32 v66, v114, v115
	v_cvt_pk_bf16_f32 v67, v116, v117
	v_cvt_pk_bf16_f32 v68, v118, v119
	v_cvt_pk_bf16_f32 v69, v120, v121
	v_cvt_pk_bf16_f32 v72, v122, v123
	v_cvt_pk_bf16_f32 v73, v124, v125
	v_cvt_pk_bf16_f32 v74, v126, v127
	v_cvt_pk_bf16_f32 v75, v128, v129
	v_cvt_pk_bf16_f32 v76, v98, v99
	v_cvt_pk_bf16_f32 v77, v100, v101
	v_cvt_pk_bf16_f32 v78, v102, v103
	v_cvt_pk_bf16_f32 v79, v104, v105
	v_cvt_pk_bf16_f32 v80, v106, v107
	v_cvt_pk_bf16_f32 v81, v108, v109
	v_cvt_pk_bf16_f32 v82, v110, v111
	v_cvt_pk_bf16_f32 v83, v112, v113
	v_add_u32_e32 v0, s0, v202
	v_permlane32_swap_b32_e32 v66, v68
	v_permlane32_swap_b32_e32 v67, v69
	v_permlane32_swap_b32_e32 v72, v74
	v_permlane32_swap_b32_e32 v73, v75
	v_permlane32_swap_b32_e32 v76, v78
	v_permlane32_swap_b32_e32 v77, v79
	v_permlane32_swap_b32_e32 v80, v82
	v_permlane32_swap_b32_e32 v81, v83
	ds_read_b64_tr_b16 v[84:85], v0 offset:0
	ds_read_b64_tr_b16 v[86:87], v0 offset:0x800
	ds_read_b64_tr_b16 v[88:89], v0 offset:0x1000
	ds_read_b64_tr_b16 v[90:91], v0 offset:0x1800
	ds_read_b64_tr_b16 v[92:93], v0 offset:0x2000
	ds_read_b64_tr_b16 v[94:95], v0 offset:0x2800
	ds_read_b64_tr_b16 v[96:97], v0 offset:0x3000
	ds_read_b64_tr_b16 v[98:99], v0 offset:0x3800
	s_waitcnt lgkmcnt(0)
	s_nop 0
	v_mfma_f32_32x32x16_bf16 v[50:65], v[66:69], v[84:87], v[50:65]
	ds_read_b64_tr_b16 v[84:85], v0 offset:0x200
	ds_read_b64_tr_b16 v[86:87], v0 offset:0xa00
	v_mfma_f32_32x32x16_bf16 v[50:65], v[72:75], v[88:91], v[50:65]
	ds_read_b64_tr_b16 v[88:89], v0 offset:0x1200
	ds_read_b64_tr_b16 v[90:91], v0 offset:0x1a00
	v_mfma_f32_32x32x16_bf16 v[50:65], v[76:79], v[92:95], v[50:65]
	ds_read_b64_tr_b16 v[92:93], v0 offset:0x2200
	ds_read_b64_tr_b16 v[94:95], v0 offset:0x2a00
	v_mfma_f32_32x32x16_bf16 v[50:65], v[80:83], v[96:99], v[50:65]
	ds_read_b64_tr_b16 v[96:97], v0 offset:0x3200
	ds_read_b64_tr_b16 v[98:99], v0 offset:0x3a00
	s_waitcnt lgkmcnt(0)
	v_mfma_f32_32x32x16_bf16 v[34:49], v[66:69], v[84:87], v[34:49]
	ds_read_b64_tr_b16 v[84:85], v0 offset:0x400
	ds_read_b64_tr_b16 v[86:87], v0 offset:0xc00
	v_mfma_f32_32x32x16_bf16 v[34:49], v[72:75], v[88:91], v[34:49]
	ds_read_b64_tr_b16 v[88:89], v0 offset:0x1400
	ds_read_b64_tr_b16 v[90:91], v0 offset:0x1c00
	v_mfma_f32_32x32x16_bf16 v[34:49], v[76:79], v[92:95], v[34:49]
	ds_read_b64_tr_b16 v[92:93], v0 offset:0x2400
	ds_read_b64_tr_b16 v[94:95], v0 offset:0x2c00
	v_mfma_f32_32x32x16_bf16 v[34:49], v[80:83], v[96:99], v[34:49]
	ds_read_b64_tr_b16 v[96:97], v0 offset:0x3400
	ds_read_b64_tr_b16 v[98:99], v0 offset:0x3c00
	s_waitcnt lgkmcnt(0)
	v_mfma_f32_32x32x16_bf16 v[18:33], v[66:69], v[84:87], v[18:33]
	ds_read_b64_tr_b16 v[84:85], v0 offset:0x600
	ds_read_b64_tr_b16 v[86:87], v0 offset:0xe00
	v_mfma_f32_32x32x16_bf16 v[18:33], v[72:75], v[88:91], v[18:33]
	ds_read_b64_tr_b16 v[88:89], v0 offset:0x1600
	ds_read_b64_tr_b16 v[90:91], v0 offset:0x1e00
	v_mfma_f32_32x32x16_bf16 v[18:33], v[76:79], v[92:95], v[18:33]
	ds_read_b64_tr_b16 v[92:93], v0 offset:0x2600
	ds_read_b64_tr_b16 v[94:95], v0 offset:0x2e00
	v_mfma_f32_32x32x16_bf16 v[18:33], v[80:83], v[96:99], v[18:33]
	ds_read_b64_tr_b16 v[96:97], v0 offset:0x3600
	ds_read_b64_tr_b16 v[98:99], v0 offset:0x3e00
	s_waitcnt lgkmcnt(0)
	v_mfma_f32_32x32x16_bf16 v[2:17], v[66:69], v[84:87], v[2:17]
	v_cmp_nlt_f32_e32 vcc, s27, v71
	v_cmp_ngt_f32_e64 s[0:1], s26, v71
	s_or_b64 s[2:3], vcc, s[0:1]
	v_mfma_f32_32x32x16_bf16 v[2:17], v[72:75], v[88:91], v[2:17]
	v_mfma_f32_32x32x16_bf16 v[2:17], v[76:79], v[92:95], v[2:17]
	v_mfma_f32_32x32x16_bf16 v[2:17], v[80:83], v[96:99], v[2:17]
	s_and_saveexec_b64 s[0:1], s[2:3]
	s_cbranch_execz .LBB0_482
	s_mov_b64 s[2:3], src_shared_base
	s_add_i32 s2, 0, 0x1d000
	s_cmp_lg_u32 s2, -1
	s_cselect_b32 s2, s2, 0
	s_cselect_b32 s3, s3, 0
	v_mov_b32_e32 v66, s2
	v_mov_b32_e32 v67, s3
	flat_store_dword v[66:67], v175 sc0 sc1
	s_waitcnt vmcnt(0)
